# MoBA gate scores: key-block-sum rows requested 5 groups ahead into free VGPRs (counted vmcnt) instead of one drained round trip per group
# speedup vs baseline: 1.0135x; 1.0135x over previous
.LBB0_788:
	s_mov_b64 s[0:1], 0x400
	s_and_b64 vcc, exec, s[4:5]
	s_cbranch_vccz .LBB0_665
	s_lshl_b32 s0, -1, s46
	s_not_b32 s6, s0
	v_readlane_b32 s0, v255, 38
	s_lshl_b32 s0, s0, 1
	v_mov_b32_e32 v17, v240
	v_readlane_b32 s100, v255, 41
	v_readlane_b32 s101, v255, 42
	s_nop 1
	s_add_u32 s0, s100, s0
	s_addc_u32 s1, s101, 0
	v_readfirstlane_b32 s2, v17
	s_ashr_i32 s2, s2, 6
	s_lshl_b32 s8, s2, 3
	v_readlane_b32 s20, v254, 9
	v_bfe_u32 v127, v17, 3, 3
	v_readlane_b32 s21, v254, 10
	s_waitcnt vmcnt(0)
	v_or_b32_e32 v2, s8, v127
	s_mov_b32 s21, s89
	s_waitcnt lgkmcnt(0)
	v_ashrrev_i32_e32 v3, 31, v2
	v_lshl_add_u64 v[4:5], v[2:3], 0, s[20:21]
	v_mov_b64_e32 v[6:7], s[0:1]
	v_mad_u64_u32 v[8:9], s[0:1], v4, s76, v[6:7]
	v_mad_i32_i24 v9, v5, s76, v9
	v_ashrrev_i32_e32 v5, 1, v2
	v_xor_b32_e32 v126, v5, v17
	v_lshlrev_b32_e32 v0, 4, v126
	v_and_b32_e32 v0, 0x70, v0
	v_and_b32_e32 v4, 7, v17
	v_lshl_add_u64 v[2:3], v[8:9], 0, v[0:1]
	v_lshlrev_b32_e32 v0, 2, v5
	s_mov_b32 s43, s89
	v_bitop3_b32 v0, v0, v4, 4 bitop3:0x6c
	s_lshl_b32 s75, s2, 5
	s_lshl_b32 s9, s2, 10
	s_lshl_b64 s[2:3], s[42:43], 1
	v_lshlrev_b32_e32 v0, 4, v0
	s_add_i32 s7, s9, 0
	v_lshl_add_u64 v[4:5], v[8:9], 0, v[0:1]
	v_lshl_add_u64 v[8:9], v[2:3], 0, s[2:3]
	s_mov_b64 s[0:1], 0x400
	s_add_i32 s10, s7, 0x2000
	v_lshl_add_u64 v[10:11], v[8:9], 0, s[0:1]
	s_mov_b32 m0, s7
	s_mov_b64 s[18:19], 0x48400
	global_load_lds_dwordx4 v[10:11], off
	v_lshl_add_u64 v[8:9], v[8:9], 0, s[18:19]
	s_mov_b32 m0, s10
	s_add_i32 s88, s42, 0x48000
	s_add_i32 s11, s7, 0x4000
	global_load_lds_dwordx4 v[8:9], off
	v_lshl_add_u64 v[8:9], v[4:5], 0, s[2:3]
	s_mov_b64 s[2:3], 0x600
	s_add_i32 s13, s7, 0x6000
	s_lshl_b64 s[4:5], s[88:89], 1
	v_lshl_add_u64 v[10:11], v[8:9], 0, s[2:3]
	s_mov_b32 m0, s11
	s_mov_b64 s[10:11], 0x48600
	s_add_i32 s14, s7, 0x8000
	global_load_lds_dwordx4 v[10:11], off
	v_lshl_add_u64 v[8:9], v[8:9], 0, s[10:11]
	s_mov_b32 m0, s13
	v_lshl_add_u64 v[2:3], v[2:3], 0, s[4:5]
	s_add_i32 s15, s7, 0xa000
	global_load_lds_dwordx4 v[8:9], off
	v_lshl_add_u64 v[8:9], v[2:3], 0, s[0:1]
	s_mov_b32 m0, s14
	v_lshl_add_u64 v[2:3], v[2:3], 0, s[18:19]
	global_load_lds_dwordx4 v[8:9], off
	s_mov_b32 m0, s15
	s_add_i32 s75, s75, s94
	s_add_i32 s16, s7, 0xc000
	v_and_b32_e32 v124, 31, v17
	global_load_lds_dwordx4 v[2:3], off
	v_lshl_add_u64 v[2:3], v[4:5], 0, s[4:5]
	s_add_i32 s17, s7, 0xe000
	v_or_b32_e32 v14, s75, v124
	v_lshl_add_u64 v[4:5], v[2:3], 0, s[2:3]
	s_mov_b32 m0, s16
	v_lshl_add_u64 v[2:3], v[2:3], 0, s[10:11]
	global_load_lds_dwordx4 v[4:5], off
	s_mov_b32 m0, s17
	v_ashrrev_i32_e32 v15, 31, v14
	s_mov_b32 s0, s20
	global_load_lds_dwordx4 v[2:3], off
	v_writelane_b32 v254, s0, 9
	v_lshl_add_u64 v[2:3], v[14:15], 0, s[20:21]
	v_bfe_u32 v125, v17, 5, 1
	v_writelane_b32 v254, s1, 10
	v_mad_u64_u32 v[4:5], s[0:1], v2, s76, v[6:7]
	v_mad_i32_i24 v5, v3, s76, v5
	v_lshlrev_b32_e32 v2, 4, v125
	v_mov_b32_e32 v3, v1
	v_lshl_add_u64 v[18:19], v[4:5], 0, v[2:3]
	global_load_dwordx4 v[2:5], v[18:19], off offset:512
	global_load_dwordx4 v[6:9], v[18:19], off offset:544
	global_load_dwordx4 v[10:13], v[18:19], off offset:576
	s_nop 0
	global_load_dwordx4 v[18:21], v[18:19], off offset:608
	s_cmp_lt_u32 s46, 4
	v_mov_b32_e32 v15, s6
	s_cbranch_scc1 .LBB0_795
	v_readlane_b32 s0, v255, 38
	s_lshl_b32 s0, s0, 2
	v_readlane_b32 s1, v255, 27
	s_add_u32 s2, s1, s0
	v_readlane_b32 s0, v255, 28
	s_addc_u32 s3, s0, 0
	s_lshl_b32 s88, s45, 12
	s_lshl_b64 s[0:1], s[88:89], 2
	v_lshlrev_b32_e32 v15, 3, v125
	s_add_u32 s0, s2, s0
	s_addc_u32 s1, s3, s1
	v_lshlrev_b32_e32 v34, 2, v15
	v_mov_b32_e32 v232, v34
	v_mov_b32_e32 v233, 0
	v_lshl_add_u64 v[232:233], s[0:1], 0, v[232:233]
	global_load_dwordx4 v[136:139], v[232:233], off offset:0
	global_load_dwordx4 v[140:143], v[232:233], off offset:16
	global_load_dwordx4 v[144:147], v[232:233], off offset:1024
	global_load_dwordx4 v[148:151], v[232:233], off offset:1040
	global_load_dwordx4 v[152:155], v[232:233], off offset:64
	global_load_dwordx4 v[156:159], v[232:233], off offset:80
	global_load_dwordx4 v[160:163], v[232:233], off offset:1088
	global_load_dwordx4 v[164:167], v[232:233], off offset:1104
	global_load_dwordx4 v[184:187], v[232:233], off offset:128
	global_load_dwordx4 v[188:191], v[232:233], off offset:144
	global_load_dwordx4 v[192:195], v[232:233], off offset:1152
	global_load_dwordx4 v[196:199], v[232:233], off offset:1168
	global_load_dwordx4 v[200:203], v[232:233], off offset:192
	global_load_dwordx4 v[204:207], v[232:233], off offset:208
	global_load_dwordx4 v[208:211], v[232:233], off offset:1216
	global_load_dwordx4 v[212:215], v[232:233], off offset:1232
	s_mov_b64 s[100:101], 0x800
	v_lshl_add_u64 v[232:233], v[232:233], 0, s[100:101]
	global_load_dwordx4 v[216:219], v[232:233], off offset:0
	global_load_dwordx4 v[220:223], v[232:233], off offset:16
	global_load_dwordx4 v[224:227], v[232:233], off offset:1024
	global_load_dwordx4 v[228:231], v[232:233], off offset:1040
	s_waitcnt vmcnt(16)
	v_mov_b64_e32 v[26:27], v[136:137]
	v_mov_b64_e32 v[28:29], v[138:139]
	v_mov_b64_e32 v[22:23], v[140:141]
	v_mov_b64_e32 v[24:25], v[142:143]
	v_mov_b64_e32 v[40:41], v[144:145]
	v_mov_b64_e32 v[42:43], v[146:147]
	v_mov_b64_e32 v[30:31], v[148:149]
	v_mov_b64_e32 v[32:33], v[150:151]
	global_load_dwordx4 v[136:139], v[232:233], off offset:64
	global_load_dwordx4 v[140:143], v[232:233], off offset:80
	global_load_dwordx4 v[144:147], v[232:233], off offset:1088
	global_load_dwordx4 v[148:151], v[232:233], off offset:1104
	v_and_b32_e32 v71, 0xffff0000, v4
	v_and_b32_e32 v70, 0xffff0000, v2
	v_lshlrev_b32_e32 v65, 16, v4
	v_lshlrev_b32_e32 v64, 16, v2
	v_lshlrev_b32_e32 v67, 16, v5
	v_lshlrev_b32_e32 v66, 16, v3
	v_and_b32_e32 v63, 0xffff0000, v8
	v_and_b32_e32 v62, 0xffff0000, v6
	v_mov_b32_e32 v35, v1
	v_lshl_add_u64 v[38:39], s[0:1], 0, v[34:35]
	v_and_b32_e32 v69, 0xffff0000, v5
	v_and_b32_e32 v68, 0xffff0000, v3
	v_lshlrev_b32_e32 v57, 16, v8
	v_lshlrev_b32_e32 v56, 16, v6
	v_lshlrev_b32_e32 v59, 16, v9
	v_lshlrev_b32_e32 v58, 16, v7
	v_and_b32_e32 v61, 0xffff0000, v9
	v_and_b32_e32 v60, 0xffff0000, v7
	v_and_b32_e32 v55, 0xffff0000, v12
	v_and_b32_e32 v54, 0xffff0000, v10
	v_and_b32_e32 v53, 0xffff0000, v13
	v_and_b32_e32 v52, 0xffff0000, v11
	v_xor_b32_e32 v15, 32, v241
	v_cmp_lt_i32_e32 vcc, v15, v242
	s_cmp_eq_u32 s46, 4
	v_pk_add_f32 v[72:73], v[24:25], v[32:33]
	v_pk_add_f32 v[74:75], v[28:29], v[42:43]
	v_pk_add_f32 v[26:27], v[26:27], v[40:41]
	v_pk_add_f32 v[24:25], v[22:23], v[30:31]
	v_cndmask_b32_e32 v15, v241, v15, vcc
	v_lshlrev_b32_e32 v15, 2, v15
	s_waitcnt vmcnt(16)
	v_mov_b64_e32 v[40:41], v[152:153]
	v_mov_b64_e32 v[42:43], v[154:155]
	v_mov_b64_e32 v[28:29], v[156:157]
	v_mov_b64_e32 v[30:31], v[158:159]
	v_mov_b64_e32 v[48:49], v[160:161]
	v_mov_b64_e32 v[50:51], v[162:163]
	v_mov_b64_e32 v[44:45], v[164:165]
	v_mov_b64_e32 v[46:47], v[166:167]
	global_load_dwordx4 v[152:155], v[232:233], off offset:128
	global_load_dwordx4 v[156:159], v[232:233], off offset:144
	global_load_dwordx4 v[160:163], v[232:233], off offset:1152
	global_load_dwordx4 v[164:167], v[232:233], off offset:1168
	v_pk_add_f32 v[76:77], v[30:31], v[46:47]
	v_pk_add_f32 v[80:81], v[42:43], v[50:51]
	v_pk_add_f32 v[22:23], v[40:41], v[48:49]
	v_pk_add_f32 v[78:79], v[28:29], v[44:45]
	s_waitcnt vmcnt(16)
	v_mov_b64_e32 v[40:41], v[184:185]
	v_mov_b64_e32 v[42:43], v[186:187]
	v_mov_b64_e32 v[28:29], v[188:189]
	v_mov_b64_e32 v[30:31], v[190:191]
	v_mov_b64_e32 v[48:49], v[192:193]
	v_mov_b64_e32 v[50:51], v[194:195]
	v_mov_b64_e32 v[44:45], v[196:197]
	v_mov_b64_e32 v[46:47], v[198:199]
	global_load_dwordx4 v[184:187], v[232:233], off offset:192
	global_load_dwordx4 v[188:191], v[232:233], off offset:208
	global_load_dwordx4 v[192:195], v[232:233], off offset:1216
	global_load_dwordx4 v[196:199], v[232:233], off offset:1232
	v_pk_add_f32 v[82:83], v[30:31], v[46:47]
	v_pk_add_f32 v[86:87], v[42:43], v[50:51]
	v_pk_add_f32 v[88:89], v[40:41], v[48:49]
	v_pk_add_f32 v[84:85], v[28:29], v[44:45]
	v_lshlrev_b32_e32 v49, 16, v12
	v_lshlrev_b32_e32 v48, 16, v10
	v_lshlrev_b32_e32 v51, 16, v13
	v_lshlrev_b32_e32 v50, 16, v11
	s_waitcnt vmcnt(16)
	v_mov_b64_e32 v[40:41], v[200:201]
	v_mov_b64_e32 v[42:43], v[202:203]
	v_mov_b64_e32 v[28:29], v[204:205]
	v_mov_b64_e32 v[30:31], v[206:207]
	v_mov_b64_e32 v[90:91], v[208:209]
	v_mov_b64_e32 v[92:93], v[210:211]
	v_mov_b64_e32 v[44:45], v[212:213]
	v_mov_b64_e32 v[46:47], v[214:215]
	s_mov_b64 s[100:101], 0x800
	v_lshl_add_u64 v[232:233], v[232:233], 0, s[100:101]
	global_load_dwordx4 v[200:203], v[232:233], off offset:0
	global_load_dwordx4 v[204:207], v[232:233], off offset:16
	global_load_dwordx4 v[208:211], v[232:233], off offset:1024
	global_load_dwordx4 v[212:215], v[232:233], off offset:1040
	v_pk_add_f32 v[94:95], v[42:43], v[92:93]
	v_pk_add_f32 v[96:97], v[40:41], v[90:91]
	v_pk_add_f32 v[90:91], v[30:31], v[46:47]
	v_pk_add_f32 v[92:93], v[28:29], v[44:45]
	v_and_b32_e32 v47, 0xffff0000, v20
	v_and_b32_e32 v46, 0xffff0000, v18
	v_lshlrev_b32_e32 v45, 16, v20
	v_lshlrev_b32_e32 v44, 16, v18
	v_lshlrev_b32_e32 v43, 16, v21
	v_lshlrev_b32_e32 v42, 16, v19
	v_and_b32_e32 v41, 0xffff0000, v21
	v_and_b32_e32 v40, 0xffff0000, v19
	s_waitcnt vmcnt(16)
	v_mov_b64_e32 v[98:99], v[216:217]
	v_mov_b64_e32 v[100:101], v[218:219]
	v_mov_b64_e32 v[28:29], v[220:221]
	v_mov_b64_e32 v[30:31], v[222:223]
	v_mov_b64_e32 v[106:107], v[224:225]
	v_mov_b64_e32 v[108:109], v[226:227]
	v_mov_b64_e32 v[102:103], v[228:229]
	v_mov_b64_e32 v[104:105], v[230:231]
	global_load_dwordx4 v[216:219], v[232:233], off offset:64
	global_load_dwordx4 v[220:223], v[232:233], off offset:80
	global_load_dwordx4 v[224:227], v[232:233], off offset:1088
	global_load_dwordx4 v[228:231], v[232:233], off offset:1104
	v_pk_add_f32 v[28:29], v[28:29], v[102:103]
	v_pk_add_f32 v[36:37], v[98:99], v[106:107]
	v_pk_add_f32 v[98:99], v[30:31], v[104:105]
	v_mov_b32_e32 v31, v26
	v_mov_b32_e32 v26, v37
	v_pk_add_f32 v[32:33], v[100:101], v[108:109]
	v_mov_b32_e32 v30, v36
	v_pk_mul_f32 v[26:27], v[26:27], v[70:71] op_sel_hi:[1,0]
	v_mov_b32_e32 v104, v98
	v_pk_fma_f32 v[26:27], v[30:31], v[64:65], v[26:27] op_sel_hi:[1,0,1]
	v_mov_b32_e32 v30, v32
	v_mov_b32_e32 v31, v74
	v_pk_fma_f32 v[100:101], v[30:31], v[66:67], v[26:27] op_sel_hi:[1,0,1]
	v_mov_b32_e32 v27, v24
	v_mov_b32_e32 v24, v29
	v_mov_b32_e32 v30, v71
	v_mov_b32_e32 v26, v28
	v_mov_b32_e32 v28, v65
	v_pk_mul_f32 v[24:25], v[24:25], v[30:31] op_sel_hi:[1,0]
	v_mov_b32_e32 v74, v33
	v_pk_fma_f32 v[102:103], v[26:27], v[28:29], v[24:25] op_sel_hi:[1,0,1]
	v_mov_b32_e32 v105, v72
	v_mov_b32_e32 v72, v67
	s_waitcnt vmcnt(16)
	v_mov_b64_e32 v[28:29], v[136:137]
	v_mov_b64_e32 v[30:31], v[138:139]
	v_mov_b64_e32 v[24:25], v[140:141]
	v_mov_b64_e32 v[26:27], v[142:143]
	v_mov_b64_e32 v[106:107], v[144:145]
	v_mov_b64_e32 v[108:109], v[146:147]
	v_mov_b64_e32 v[112:113], v[148:149]
	v_mov_b64_e32 v[114:115], v[150:151]
	global_load_dwordx4 v[136:139], v[232:233], off offset:128
	global_load_dwordx4 v[140:143], v[232:233], off offset:144
	global_load_dwordx4 v[144:147], v[232:233], off offset:1152
	global_load_dwordx4 v[148:151], v[232:233], off offset:1168
	v_pk_add_f32 v[28:29], v[28:29], v[106:107]
	v_pk_add_f32 v[110:111], v[30:31], v[108:109]
	v_pk_add_f32 v[108:109], v[24:25], v[112:113]
	v_mov_b32_e32 v113, v22
	v_mov_b32_e32 v22, v29
	v_pk_add_f32 v[106:107], v[26:27], v[114:115]
	v_mov_b32_e32 v112, v28
	v_pk_mul_f32 v[114:115], v[22:23], v[62:63] op_sel_hi:[1,0]
	s_waitcnt vmcnt(16)
	v_mov_b64_e32 v[26:27], v[152:153]
	v_mov_b64_e32 v[28:29], v[154:155]
	v_mov_b64_e32 v[22:23], v[156:157]
	v_mov_b64_e32 v[24:25], v[158:159]
	v_mov_b64_e32 v[116:117], v[160:161]
	v_mov_b64_e32 v[118:119], v[162:163]
	v_mov_b64_e32 v[30:31], v[164:165]
	v_mov_b64_e32 v[32:33], v[166:167]
	global_load_dwordx4 v[152:155], v[232:233], off offset:192
	global_load_dwordx4 v[156:159], v[232:233], off offset:208
	global_load_dwordx4 v[160:163], v[232:233], off offset:1216
	global_load_dwordx4 v[164:167], v[232:233], off offset:1232
	v_pk_add_f32 v[120:121], v[28:29], v[118:119]
	v_pk_add_f32 v[122:123], v[26:27], v[116:117]
	v_pk_add_f32 v[116:117], v[24:25], v[32:33]
	v_pk_add_f32 v[118:119], v[22:23], v[30:31]
	s_nop 0
	s_mov_b64 s[0:1], 0x1000
	s_waitcnt vmcnt(16)
	v_mov_b64_e32 v[30:31], v[184:185]
	v_mov_b64_e32 v[32:33], v[186:187]
	v_mov_b64_e32 v[22:23], v[188:189]
	v_mov_b64_e32 v[24:25], v[190:191]
	v_mov_b64_e32 v[34:35], v[192:193]
	v_mov_b64_e32 v[36:37], v[194:195]
	v_mov_b64_e32 v[26:27], v[196:197]
	v_mov_b64_e32 v[28:29], v[198:199]
	s_mov_b64 s[100:101], 0x800
	v_lshl_add_u64 v[232:233], v[232:233], 0, s[100:101]
	global_load_dwordx4 v[184:187], v[232:233], off offset:0
	global_load_dwordx4 v[188:191], v[232:233], off offset:16
	global_load_dwordx4 v[192:195], v[232:233], off offset:1024
	global_load_dwordx4 v[196:199], v[232:233], off offset:1040
	v_pk_add_f32 v[24:25], v[24:25], v[28:29]
	v_pk_add_f32 v[30:31], v[30:31], v[34:35]
	v_pk_add_f32 v[22:23], v[22:23], v[26:27]
	v_pk_fma_f32 v[26:27], v[74:75], v[68:69], v[100:101] op_sel_hi:[1,0,1]
	v_pk_fma_f32 v[28:29], v[104:105], v[72:73], v[102:103] op_sel_hi:[1,0,1]
	v_mov_b32_e32 v72, v99
	v_mov_b32_e32 v34, v69
	v_pk_add_f32 v[26:27], v[26:27], 0 op_sel_hi:[1,0]
	v_pk_fma_f32 v[28:29], v[72:73], v[34:35], v[28:29] op_sel_hi:[1,0,1]
	v_mov_b32_e32 v34, v110
	v_pk_add_f32 v[26:27], v[26:27], v[28:29]
	v_pk_fma_f32 v[28:29], v[112:113], v[56:57], v[114:115] op_sel_hi:[1,0,1]
	v_mov_b32_e32 v35, v80
	v_pk_fma_f32 v[28:29], v[34:35], v[58:59], v[28:29] op_sel_hi:[1,0,1]
	v_mov_b32_e32 v80, v111
	v_pk_fma_f32 v[28:29], v[80:81], v[60:61], v[28:29] op_sel_hi:[1,0,1]
	v_pk_add_f32 v[32:33], v[32:33], v[36:37]
	v_pk_add_f32 v[26:27], v[26:27], v[28:29]
	v_mov_b32_e32 v29, v78
	v_mov_b32_e32 v78, v109
	v_mov_b32_e32 v36, v63
	v_mov_b32_e32 v28, v108
	v_mov_b32_e32 v34, v57
	v_pk_mul_f32 v[36:37], v[78:79], v[36:37] op_sel_hi:[1,0]
	s_nop 0
	v_pk_fma_f32 v[28:29], v[28:29], v[34:35], v[36:37] op_sel_hi:[1,0,1]
	v_mov_b32_e32 v34, v106
	v_mov_b32_e32 v35, v76
	v_mov_b32_e32 v36, v59
	v_pk_fma_f32 v[28:29], v[34:35], v[36:37], v[28:29] op_sel_hi:[1,0,1]
	v_mov_b32_e32 v76, v107
	v_mov_b32_e32 v34, v61
	v_pk_fma_f32 v[28:29], v[76:77], v[34:35], v[28:29] op_sel_hi:[1,0,1]
	v_mov_b32_e32 v36, v55
	v_pk_add_f32 v[26:27], v[26:27], v[28:29]
	v_mov_b32_e32 v29, v88
	v_mov_b32_e32 v88, v123
	v_mov_b32_e32 v28, v122
	v_pk_mul_f32 v[34:35], v[88:89], v[54:55] op_sel_hi:[1,0]
	s_nop 0
	v_pk_fma_f32 v[28:29], v[28:29], v[48:49], v[34:35] op_sel_hi:[1,0,1]
	v_mov_b32_e32 v34, v120
	v_mov_b32_e32 v35, v86
	v_pk_fma_f32 v[28:29], v[34:35], v[50:51], v[28:29] op_sel_hi:[1,0,1]
	v_mov_b32_e32 v86, v121
	v_pk_fma_f32 v[28:29], v[86:87], v[52:53], v[28:29] op_sel_hi:[1,0,1]
	v_mov_b32_e32 v34, v49
	v_pk_add_f32 v[26:27], v[26:27], v[28:29]
	v_mov_b32_e32 v29, v84
	v_mov_b32_e32 v84, v119
	v_mov_b32_e32 v28, v118
	v_pk_mul_f32 v[36:37], v[84:85], v[36:37] op_sel_hi:[1,0]
	s_nop 0
	v_pk_fma_f32 v[28:29], v[28:29], v[34:35], v[36:37] op_sel_hi:[1,0,1]
	v_mov_b32_e32 v34, v116
	v_mov_b32_e32 v35, v82
	v_mov_b32_e32 v36, v51
	v_pk_fma_f32 v[28:29], v[34:35], v[36:37], v[28:29] op_sel_hi:[1,0,1]
	v_mov_b32_e32 v82, v117
	v_mov_b32_e32 v34, v53
	v_pk_fma_f32 v[28:29], v[82:83], v[34:35], v[28:29] op_sel_hi:[1,0,1]
	s_nop 0
	v_pk_add_f32 v[26:27], v[26:27], v[28:29]
	v_mov_b32_e32 v29, v96
	v_mov_b32_e32 v96, v31
	v_mov_b32_e32 v28, v30
	v_pk_mul_f32 v[30:31], v[96:97], v[46:47] op_sel_hi:[1,0]
	s_nop 0
	v_pk_fma_f32 v[28:29], v[28:29], v[44:45], v[30:31] op_sel_hi:[1,0,1]
	v_mov_b32_e32 v30, v32
	v_mov_b32_e32 v31, v94
	v_pk_fma_f32 v[28:29], v[30:31], v[42:43], v[28:29] op_sel_hi:[1,0,1]
	v_mov_b32_e32 v94, v33
	v_pk_fma_f32 v[28:29], v[94:95], v[40:41], v[28:29] op_sel_hi:[1,0,1]
	v_mov_b32_e32 v30, v47
	v_pk_add_f32 v[26:27], v[26:27], v[28:29]
	v_mov_b32_e32 v29, v92
	v_mov_b32_e32 v92, v23
	v_mov_b32_e32 v28, v22
	v_mov_b32_e32 v22, v45
	v_pk_mul_f32 v[30:31], v[92:93], v[30:31] op_sel_hi:[1,0]
	s_nop 0
	v_pk_fma_f32 v[22:23], v[28:29], v[22:23], v[30:31] op_sel_hi:[1,0,1]
	v_mov_b32_e32 v28, v24
	v_mov_b32_e32 v29, v90
	v_mov_b32_e32 v24, v43
	v_pk_fma_f32 v[22:23], v[28:29], v[24:25], v[22:23] op_sel_hi:[1,0,1]
	v_mov_b32_e32 v90, v25
	v_mov_b32_e32 v24, v41
	v_pk_fma_f32 v[22:23], v[90:91], v[24:25], v[22:23] op_sel_hi:[1,0,1]
	v_lshl_add_u64 v[24:25], v[38:39], 0, s[0:1]
	s_mov_b64 s[0:1], 0x1400
	v_pk_add_f32 v[72:73], v[26:27], v[22:23]
	v_lshl_add_u64 v[22:23], v[38:39], 0, s[0:1]
	s_movk_i32 s0, 0x1000
	v_add_co_u32_e32 v30, vcc, s0, v38
	s_mov_b64 s[0:1], 0x1040
	s_nop 0
	v_addc_co_u32_e32 v31, vcc, 0, v39, vcc
	s_nop 0
	ds_bpermute_b32 v75, v15, v73
	ds_bpermute_b32 v74, v15, v72
	s_waitcnt vmcnt(16)
	v_mov_b64_e32 v[26:27], v[200:201]
	v_mov_b64_e32 v[28:29], v[202:203]
	v_mov_b64_e32 v[32:33], v[204:205]
	v_mov_b64_e32 v[34:35], v[206:207]
	v_mov_b64_e32 v[76:77], v[208:209]
	v_mov_b64_e32 v[78:79], v[210:211]
	v_mov_b64_e32 v[22:23], v[212:213]
	v_mov_b64_e32 v[24:25], v[214:215]
	global_load_dwordx4 v[200:203], v[232:233], off offset:64
	global_load_dwordx4 v[204:207], v[232:233], off offset:80
	global_load_dwordx4 v[208:211], v[232:233], off offset:1088
	global_load_dwordx4 v[212:215], v[232:233], off offset:1104
	v_pk_add_f32 v[26:27], v[26:27], v[76:77]
	v_pk_add_f32 v[22:23], v[32:33], v[22:23]
	v_mul_f32_e32 v27, v27, v70
	v_pk_add_f32 v[28:29], v[28:29], v[78:79]
	v_fmac_f32_e32 v27, v26, v64
	v_mul_f32_e32 v23, v23, v71
	v_pk_add_f32 v[24:25], v[34:35], v[24:25]
	v_fmac_f32_e32 v27, v28, v66
	v_fmac_f32_e32 v23, v22, v65
	v_fmac_f32_e32 v27, v29, v68
	v_fmac_f32_e32 v23, v24, v67
	v_add_f32_e32 v26, 0, v27
	v_fmac_f32_e32 v23, v25, v69
	v_add_f32_e32 v80, v26, v23
	v_lshl_add_u64 v[26:27], v[38:39], 0, s[0:1]
	s_mov_b64 s[0:1], 0x1440
	s_nop 0
	v_lshl_add_u64 v[36:37], v[38:39], 0, s[0:1]
	s_mov_b64 s[0:1], 0x1080
	s_waitcnt vmcnt(16)
	v_mov_b64_e32 v[22:23], v[216:217]
	v_mov_b64_e32 v[24:25], v[218:219]
	v_mov_b64_e32 v[26:27], v[220:221]
	v_mov_b64_e32 v[28:29], v[222:223]
	v_mov_b64_e32 v[32:33], v[224:225]
	v_mov_b64_e32 v[34:35], v[226:227]
	v_mov_b64_e32 v[76:77], v[228:229]
	v_mov_b64_e32 v[78:79], v[230:231]
	global_load_dwordx4 v[216:219], v[232:233], off offset:128
	global_load_dwordx4 v[220:223], v[232:233], off offset:144
	global_load_dwordx4 v[224:227], v[232:233], off offset:1152
	global_load_dwordx4 v[228:231], v[232:233], off offset:1168
	v_pk_add_f32 v[22:23], v[22:23], v[32:33]
	s_nop 0
	v_mul_f32_e32 v23, v23, v62
	v_pk_add_f32 v[24:25], v[24:25], v[34:35]
	v_fmac_f32_e32 v23, v22, v56
	v_fmac_f32_e32 v23, v24, v58
	v_pk_add_f32 v[26:27], v[26:27], v[76:77]
	v_fmac_f32_e32 v23, v25, v60
	v_add_f32_e32 v22, v80, v23
	v_mul_f32_e32 v23, v27, v63
	v_pk_add_f32 v[28:29], v[28:29], v[78:79]
	v_fmac_f32_e32 v23, v26, v57
	v_fmac_f32_e32 v23, v28, v59
	v_fmac_f32_e32 v23, v29, v61
	v_lshl_add_u64 v[26:27], v[38:39], 0, s[0:1]
	s_mov_b64 s[0:1], 0x1480
	v_add_f32_e32 v80, v22, v23
	s_nop 0
	v_lshl_add_u64 v[36:37], v[38:39], 0, s[0:1]
	s_mov_b64 s[0:1], 0x10c0
	s_waitcnt vmcnt(16)
	v_mov_b64_e32 v[22:23], v[136:137]
	v_mov_b64_e32 v[24:25], v[138:139]
	v_mov_b64_e32 v[26:27], v[140:141]
	v_mov_b64_e32 v[28:29], v[142:143]
	v_mov_b64_e32 v[32:33], v[144:145]
	v_mov_b64_e32 v[34:35], v[146:147]
	v_mov_b64_e32 v[76:77], v[148:149]
	v_mov_b64_e32 v[78:79], v[150:151]
	global_load_dwordx4 v[136:139], v[232:233], off offset:192
	global_load_dwordx4 v[140:143], v[232:233], off offset:208
	global_load_dwordx4 v[144:147], v[232:233], off offset:1216
	global_load_dwordx4 v[148:151], v[232:233], off offset:1232
	v_pk_add_f32 v[22:23], v[22:23], v[32:33]
	s_nop 0
	v_mul_f32_e32 v23, v23, v54
	v_pk_add_f32 v[24:25], v[24:25], v[34:35]
	v_fmac_f32_e32 v23, v22, v48
	v_fmac_f32_e32 v23, v24, v50
	v_pk_add_f32 v[26:27], v[26:27], v[76:77]
	v_fmac_f32_e32 v23, v25, v52
	v_add_f32_e32 v22, v80, v23
	v_mul_f32_e32 v23, v27, v55
	v_pk_add_f32 v[28:29], v[28:29], v[78:79]
	v_fmac_f32_e32 v23, v26, v49
	v_fmac_f32_e32 v23, v28, v51
	v_fmac_f32_e32 v23, v29, v53
	v_lshl_add_u64 v[26:27], v[38:39], 0, s[0:1]
	s_mov_b64 s[0:1], 0x14c0
	v_add_f32_e32 v80, v22, v23
	s_nop 0
	v_lshl_add_u64 v[36:37], v[38:39], 0, s[0:1]
	s_mov_b64 s[0:1], 0x1800
	s_waitcnt vmcnt(16)
	v_mov_b64_e32 v[22:23], v[152:153]
	v_mov_b64_e32 v[24:25], v[154:155]
	v_mov_b64_e32 v[26:27], v[156:157]
	v_mov_b64_e32 v[28:29], v[158:159]
	v_mov_b64_e32 v[32:33], v[160:161]
	v_mov_b64_e32 v[34:35], v[162:163]
	v_mov_b64_e32 v[76:77], v[164:165]
	v_mov_b64_e32 v[78:79], v[166:167]
	s_mov_b64 s[100:101], 0x800
	v_lshl_add_u64 v[232:233], v[232:233], 0, s[100:101]
	global_load_dwordx4 v[152:155], v[232:233], off offset:0
	global_load_dwordx4 v[156:159], v[232:233], off offset:16
	global_load_dwordx4 v[160:163], v[232:233], off offset:1024
	global_load_dwordx4 v[164:167], v[232:233], off offset:1040
	v_pk_add_f32 v[22:23], v[22:23], v[32:33]
	s_nop 0
	v_mul_f32_e32 v23, v23, v46
	v_pk_add_f32 v[24:25], v[24:25], v[34:35]
	v_fmac_f32_e32 v23, v22, v44
	v_fmac_f32_e32 v23, v24, v42
	v_pk_add_f32 v[26:27], v[26:27], v[76:77]
	v_fmac_f32_e32 v23, v25, v40
	v_add_f32_e32 v22, v80, v23
	v_mul_f32_e32 v23, v27, v47
	v_pk_add_f32 v[28:29], v[28:29], v[78:79]
	v_fmac_f32_e32 v23, v26, v45
	v_fmac_f32_e32 v23, v28, v43
	v_fmac_f32_e32 v23, v29, v41
	v_lshl_add_u64 v[26:27], v[38:39], 0, s[0:1]
	s_mov_b64 s[0:1], 0x1c00
	v_add_f32_e32 v76, v22, v23
	v_lshl_add_u64 v[36:37], v[38:39], 0, s[0:1]
	s_nop 0
	s_nop 0
	s_mov_b64 s[0:1], 0x1840
	ds_bpermute_b32 v77, v15, v76
	s_waitcnt vmcnt(16)
	v_mov_b64_e32 v[22:23], v[184:185]
	v_mov_b64_e32 v[24:25], v[186:187]
	v_mov_b64_e32 v[26:27], v[188:189]
	v_mov_b64_e32 v[28:29], v[190:191]
	v_mov_b64_e32 v[32:33], v[192:193]
	v_mov_b64_e32 v[34:35], v[194:195]
	v_mov_b64_e32 v[78:79], v[196:197]
	v_mov_b64_e32 v[80:81], v[198:199]
	global_load_dwordx4 v[184:187], v[232:233], off offset:64
	global_load_dwordx4 v[188:191], v[232:233], off offset:80
	global_load_dwordx4 v[192:195], v[232:233], off offset:1088
	global_load_dwordx4 v[196:199], v[232:233], off offset:1104
	v_pk_add_f32 v[22:23], v[22:23], v[32:33]
	s_nop 0
	v_mul_f32_e32 v23, v23, v70
	v_pk_add_f32 v[24:25], v[24:25], v[34:35]
	v_fmac_f32_e32 v23, v22, v64
	v_fmac_f32_e32 v23, v24, v66
	v_pk_add_f32 v[26:27], v[26:27], v[78:79]
	v_fmac_f32_e32 v23, v25, v68
	v_add_f32_e32 v22, 0, v23
	v_mul_f32_e32 v23, v27, v71
	v_pk_add_f32 v[28:29], v[28:29], v[80:81]
	v_fmac_f32_e32 v23, v26, v65
	v_fmac_f32_e32 v23, v28, v67
	v_fmac_f32_e32 v23, v29, v69
	v_lshl_add_u64 v[26:27], v[38:39], 0, s[0:1]
	s_mov_b64 s[0:1], 0x1c40
	v_add_f32_e32 v82, v22, v23
	s_nop 0
	v_lshl_add_u64 v[36:37], v[38:39], 0, s[0:1]
	s_mov_b64 s[0:1], 0x1880
	s_waitcnt vmcnt(16)
	v_mov_b64_e32 v[22:23], v[200:201]
	v_mov_b64_e32 v[24:25], v[202:203]
	v_mov_b64_e32 v[26:27], v[204:205]
	v_mov_b64_e32 v[28:29], v[206:207]
	v_mov_b64_e32 v[32:33], v[208:209]
	v_mov_b64_e32 v[34:35], v[210:211]
	v_mov_b64_e32 v[78:79], v[212:213]
	v_mov_b64_e32 v[80:81], v[214:215]
	global_load_dwordx4 v[200:203], v[232:233], off offset:128
	global_load_dwordx4 v[204:207], v[232:233], off offset:144
	global_load_dwordx4 v[208:211], v[232:233], off offset:1152
	global_load_dwordx4 v[212:215], v[232:233], off offset:1168
	v_pk_add_f32 v[22:23], v[22:23], v[32:33]
	s_nop 0
	v_mul_f32_e32 v23, v23, v62
	v_pk_add_f32 v[24:25], v[24:25], v[34:35]
	v_fmac_f32_e32 v23, v22, v56
	v_fmac_f32_e32 v23, v24, v58
	v_pk_add_f32 v[26:27], v[26:27], v[78:79]
	v_fmac_f32_e32 v23, v25, v60
	v_add_f32_e32 v22, v82, v23
	v_mul_f32_e32 v23, v27, v63
	v_pk_add_f32 v[28:29], v[28:29], v[80:81]
	v_fmac_f32_e32 v23, v26, v57
	v_fmac_f32_e32 v23, v28, v59
	v_fmac_f32_e32 v23, v29, v61
	v_lshl_add_u64 v[26:27], v[38:39], 0, s[0:1]
	s_mov_b64 s[0:1], 0x1c80
	v_add_f32_e32 v82, v22, v23
	s_nop 0
	v_lshl_add_u64 v[36:37], v[38:39], 0, s[0:1]
	s_mov_b64 s[0:1], 0x18c0
	s_waitcnt vmcnt(16)
	v_mov_b64_e32 v[22:23], v[216:217]
	v_mov_b64_e32 v[24:25], v[218:219]
	v_mov_b64_e32 v[26:27], v[220:221]
	v_mov_b64_e32 v[28:29], v[222:223]
	v_mov_b64_e32 v[32:33], v[224:225]
	v_mov_b64_e32 v[34:35], v[226:227]
	v_mov_b64_e32 v[78:79], v[228:229]
	v_mov_b64_e32 v[80:81], v[230:231]
	global_load_dwordx4 v[216:219], v[232:233], off offset:192
	global_load_dwordx4 v[220:223], v[232:233], off offset:208
	global_load_dwordx4 v[224:227], v[232:233], off offset:1216
	global_load_dwordx4 v[228:231], v[232:233], off offset:1232
	v_pk_add_f32 v[22:23], v[22:23], v[32:33]
	s_nop 0
	v_mul_f32_e32 v23, v23, v54
	v_pk_add_f32 v[24:25], v[24:25], v[34:35]
	v_fmac_f32_e32 v23, v22, v48
	v_fmac_f32_e32 v23, v24, v50
	v_pk_add_f32 v[26:27], v[26:27], v[78:79]
	v_fmac_f32_e32 v23, v25, v52
	v_add_f32_e32 v22, v82, v23
	v_mul_f32_e32 v23, v27, v55
	v_pk_add_f32 v[28:29], v[28:29], v[80:81]
	v_fmac_f32_e32 v23, v26, v49
	v_fmac_f32_e32 v23, v28, v51
	v_fmac_f32_e32 v23, v29, v53
	v_add_f32_e32 v78, v22, v23
	v_lshl_add_u64 v[22:23], v[38:39], 0, s[0:1]
	s_mov_b64 s[0:1], 0x1cc0
	v_lshl_add_u64 v[32:33], v[38:39], 0, s[0:1]
	s_nop 0
	s_nop 0
	s_nop 0
	s_waitcnt vmcnt(16)
	v_mov_b64_e32 v[26:27], v[136:137]
	v_mov_b64_e32 v[28:29], v[138:139]
	v_mov_b64_e32 v[22:23], v[140:141]
	v_mov_b64_e32 v[24:25], v[142:143]
	v_mov_b64_e32 v[34:35], v[144:145]
	v_mov_b64_e32 v[36:37], v[146:147]
	v_mov_b64_e32 v[30:31], v[148:149]
	v_mov_b64_e32 v[32:33], v[150:151]
	s_mov_b64 s[100:101], 0x800
	v_lshl_add_u64 v[232:233], v[232:233], 0, s[100:101]
	global_load_dwordx4 v[136:139], v[232:233], off offset:0
	global_load_dwordx4 v[140:143], v[232:233], off offset:16
	global_load_dwordx4 v[144:147], v[232:233], off offset:1024
	global_load_dwordx4 v[148:151], v[232:233], off offset:1040
	v_pk_add_f32 v[26:27], v[26:27], v[34:35]
	v_pk_add_f32 v[22:23], v[22:23], v[30:31]
	v_mul_f32_e32 v27, v27, v46
	v_pk_add_f32 v[28:29], v[28:29], v[36:37]
	v_fmac_f32_e32 v27, v26, v44
	v_mul_f32_e32 v23, v23, v47
	v_pk_add_f32 v[24:25], v[24:25], v[32:33]
	v_fmac_f32_e32 v27, v28, v42
	v_fmac_f32_e32 v23, v22, v45
	v_fmac_f32_e32 v27, v29, v40
	v_fmac_f32_e32 v23, v24, v43
	v_add_f32_e32 v26, v78, v27
	v_fmac_f32_e32 v23, v25, v41
	v_add_f32_e32 v24, v26, v23
	ds_bpermute_b32 v25, v15, v24
	v_mov_b32_e32 v27, 0xff800000
	v_mov_b32_e32 v26, 0xff800000
	s_cbranch_scc1 .LBB0_846
	s_mov_b64 s[0:1], 0x2000
	v_add_co_u32_e32 v22, vcc, 0x2000, v38
	v_lshl_add_u64 v[32:33], v[38:39], 0, s[0:1]
	s_mov_b64 s[0:1], 0x2400
	v_addc_co_u32_e32 v23, vcc, 0, v39, vcc
	v_lshl_add_u64 v[36:37], v[38:39], 0, s[0:1]
	s_nop 0
	s_nop 0
	s_mov_b64 s[0:1], 0x2040
	s_waitcnt vmcnt(16)
	v_mov_b64_e32 v[28:29], v[152:153]
	v_mov_b64_e32 v[30:31], v[154:155]
	v_mov_b64_e32 v[32:33], v[156:157]
	v_mov_b64_e32 v[34:35], v[158:159]
	v_mov_b64_e32 v[78:79], v[160:161]
	v_mov_b64_e32 v[80:81], v[162:163]
	v_mov_b64_e32 v[82:83], v[164:165]
	v_mov_b64_e32 v[84:85], v[166:167]
	global_load_dwordx4 v[152:155], v[232:233], off offset:64
	global_load_dwordx4 v[156:159], v[232:233], off offset:80
	global_load_dwordx4 v[160:163], v[232:233], off offset:1088
	global_load_dwordx4 v[164:167], v[232:233], off offset:1104
	v_pk_add_f32 v[28:29], v[28:29], v[78:79]
	v_pk_add_f32 v[32:33], v[32:33], v[82:83]
	v_pk_add_f32 v[30:31], v[30:31], v[80:81]
	v_mov_b32_e32 v37, v32
	v_mov_b32_e32 v32, v29
	v_pk_add_f32 v[34:35], v[34:35], v[84:85]
	v_mov_b32_e32 v36, v28
	v_pk_mul_f32 v[28:29], v[32:33], v[70:71]
	v_mov_b32_e32 v32, v30
	v_pk_fma_f32 v[28:29], v[36:37], v[64:65], v[28:29]
	v_mov_b32_e32 v33, v34
	v_pk_fma_f32 v[28:29], v[32:33], v[66:67], v[28:29]
	v_mov_b32_e32 v34, v31
	v_pk_fma_f32 v[28:29], v[34:35], v[68:69], v[28:29]
	v_lshl_add_u64 v[32:33], v[38:39], 0, s[0:1]
	v_add_f32_e32 v26, 0, v28
	s_mov_b64 s[0:1], 0x2440
	v_add_f32_e32 v26, v26, v29
	s_nop 0
	v_lshl_add_u64 v[36:37], v[38:39], 0, s[0:1]
	s_mov_b64 s[0:1], 0x2080
	s_waitcnt vmcnt(16)
	v_mov_b64_e32 v[28:29], v[184:185]
	v_mov_b64_e32 v[30:31], v[186:187]
	v_mov_b64_e32 v[32:33], v[188:189]
	v_mov_b64_e32 v[34:35], v[190:191]
	v_mov_b64_e32 v[78:79], v[192:193]
	v_mov_b64_e32 v[80:81], v[194:195]
	v_mov_b64_e32 v[82:83], v[196:197]
	v_mov_b64_e32 v[84:85], v[198:199]
	global_load_dwordx4 v[184:187], v[232:233], off offset:128
	global_load_dwordx4 v[188:191], v[232:233], off offset:144
	global_load_dwordx4 v[192:195], v[232:233], off offset:1152
	global_load_dwordx4 v[196:199], v[232:233], off offset:1168
	v_pk_add_f32 v[28:29], v[28:29], v[78:79]
	v_pk_add_f32 v[32:33], v[32:33], v[82:83]
	v_pk_add_f32 v[30:31], v[30:31], v[80:81]
	v_mov_b32_e32 v37, v32
	v_mov_b32_e32 v32, v29
	v_pk_add_f32 v[34:35], v[34:35], v[84:85]
	v_mov_b32_e32 v36, v28
	v_pk_mul_f32 v[28:29], v[32:33], v[62:63]
	v_mov_b32_e32 v32, v30
	v_pk_fma_f32 v[28:29], v[36:37], v[56:57], v[28:29]
	v_mov_b32_e32 v33, v34
	v_pk_fma_f32 v[28:29], v[32:33], v[58:59], v[28:29]
	v_mov_b32_e32 v34, v31
	v_pk_fma_f32 v[28:29], v[34:35], v[60:61], v[28:29]
	v_lshl_add_u64 v[32:33], v[38:39], 0, s[0:1]
	v_add_f32_e32 v26, v26, v28
	s_mov_b64 s[0:1], 0x2480
	v_add_f32_e32 v26, v26, v29
	s_nop 0
	v_lshl_add_u64 v[36:37], v[38:39], 0, s[0:1]
	s_mov_b64 s[0:1], 0x20c0
	s_waitcnt vmcnt(16)
	v_mov_b64_e32 v[28:29], v[200:201]
	v_mov_b64_e32 v[30:31], v[202:203]
	v_mov_b64_e32 v[32:33], v[204:205]
	v_mov_b64_e32 v[34:35], v[206:207]
	v_mov_b64_e32 v[78:79], v[208:209]
	v_mov_b64_e32 v[80:81], v[210:211]
	v_mov_b64_e32 v[82:83], v[212:213]
	v_mov_b64_e32 v[84:85], v[214:215]
	global_load_dwordx4 v[200:203], v[232:233], off offset:192
	global_load_dwordx4 v[204:207], v[232:233], off offset:208
	global_load_dwordx4 v[208:211], v[232:233], off offset:1216
	global_load_dwordx4 v[212:215], v[232:233], off offset:1232
	v_pk_add_f32 v[28:29], v[28:29], v[78:79]
	v_pk_add_f32 v[32:33], v[32:33], v[82:83]
	v_pk_add_f32 v[30:31], v[30:31], v[80:81]
	v_mov_b32_e32 v37, v32
	v_mov_b32_e32 v32, v29
	v_pk_add_f32 v[34:35], v[34:35], v[84:85]
	v_mov_b32_e32 v36, v28
	v_pk_mul_f32 v[28:29], v[32:33], v[54:55]
	v_mov_b32_e32 v32, v30
	v_pk_fma_f32 v[28:29], v[36:37], v[48:49], v[28:29]
	v_mov_b32_e32 v33, v34
	v_pk_fma_f32 v[28:29], v[32:33], v[50:51], v[28:29]
	v_mov_b32_e32 v34, v31
	v_pk_fma_f32 v[28:29], v[34:35], v[52:53], v[28:29]
	v_lshl_add_u64 v[32:33], v[38:39], 0, s[0:1]
	v_add_f32_e32 v26, v26, v28
	s_mov_b64 s[0:1], 0x24c0
	v_add_f32_e32 v26, v26, v29
	s_nop 0
	v_lshl_add_u64 v[36:37], v[38:39], 0, s[0:1]
	s_waitcnt vmcnt(16)
	v_mov_b64_e32 v[28:29], v[216:217]
	v_mov_b64_e32 v[30:31], v[218:219]
	v_mov_b64_e32 v[32:33], v[220:221]
	v_mov_b64_e32 v[34:35], v[222:223]
	v_mov_b64_e32 v[78:79], v[224:225]
	v_mov_b64_e32 v[80:81], v[226:227]
	v_mov_b64_e32 v[82:83], v[228:229]
	v_mov_b64_e32 v[84:85], v[230:231]
	s_mov_b64 s[100:101], 0x800
	v_lshl_add_u64 v[232:233], v[232:233], 0, s[100:101]
	global_load_dwordx4 v[216:219], v[232:233], off offset:0
	global_load_dwordx4 v[220:223], v[232:233], off offset:16
	global_load_dwordx4 v[224:227], v[232:233], off offset:1024
	global_load_dwordx4 v[228:231], v[232:233], off offset:1040
	v_pk_add_f32 v[28:29], v[28:29], v[78:79]
	v_pk_add_f32 v[32:33], v[32:33], v[82:83]
	v_pk_add_f32 v[22:23], v[30:31], v[80:81]
	v_pk_add_f32 v[30:31], v[34:35], v[84:85]
	v_mov_b32_e32 v35, v32
	v_mov_b32_e32 v32, v29
	v_mov_b32_e32 v34, v28
	v_pk_mul_f32 v[28:29], v[32:33], v[46:47]
	v_mov_b32_e32 v32, v22
	v_pk_fma_f32 v[28:29], v[34:35], v[44:45], v[28:29]
	v_mov_b32_e32 v33, v30
	v_pk_fma_f32 v[28:29], v[32:33], v[42:43], v[28:29]
	v_mov_b32_e32 v30, v23
	v_pk_fma_f32 v[22:23], v[30:31], v[40:41], v[28:29]
	s_nop 0
	v_add_f32_e32 v22, v26, v22
	v_add_f32_e32 v22, v22, v23
	ds_bpermute_b32 v23, v15, v22
	s_waitcnt lgkmcnt(0)
	v_add_f32_e32 v26, v22, v23
	s_cmp_lt_u32 s46, 6
	s_cbranch_scc0 .LBB0_847

.LBB0_793:
	s_mov_b64 s[0:1], 0x3000
	v_add_co_u32_e32 v22, vcc, 0x3000, v38
	v_lshl_add_u64 v[32:33], v[38:39], 0, s[0:1]
	s_mov_b64 s[0:1], 0x3400
	v_addc_co_u32_e32 v23, vcc, 0, v39, vcc
	v_lshl_add_u64 v[36:37], v[38:39], 0, s[0:1]
	s_nop 0
	s_nop 0
	s_mov_b64 s[0:1], 0x3040
	s_waitcnt vmcnt(12)
	v_mov_b64_e32 v[28:29], v[216:217]
	v_mov_b64_e32 v[30:31], v[218:219]
	v_mov_b64_e32 v[32:33], v[220:221]
	v_mov_b64_e32 v[34:35], v[222:223]
	v_mov_b64_e32 v[78:79], v[224:225]
	v_mov_b64_e32 v[80:81], v[226:227]
	v_mov_b64_e32 v[82:83], v[228:229]
	v_mov_b64_e32 v[84:85], v[230:231]
	v_pk_add_f32 v[28:29], v[28:29], v[78:79]
	v_pk_add_f32 v[32:33], v[32:33], v[82:83]
	v_pk_add_f32 v[30:31], v[30:31], v[80:81]
	v_mov_b32_e32 v37, v32
	v_mov_b32_e32 v32, v29
	v_pk_add_f32 v[34:35], v[34:35], v[84:85]
	v_mov_b32_e32 v36, v28
	v_pk_mul_f32 v[28:29], v[32:33], v[70:71]
	v_mov_b32_e32 v32, v30
	v_pk_fma_f32 v[28:29], v[36:37], v[64:65], v[28:29]
	v_mov_b32_e32 v33, v34
	v_pk_fma_f32 v[28:29], v[32:33], v[66:67], v[28:29]
	v_mov_b32_e32 v34, v31
	v_pk_fma_f32 v[28:29], v[34:35], v[68:69], v[28:29]
	v_lshl_add_u64 v[32:33], v[38:39], 0, s[0:1]
	v_add_f32_e32 v28, 0, v28
	s_mov_b64 s[0:1], 0x3440
	v_add_f32_e32 v78, v28, v29
	s_nop 0
	v_lshl_add_u64 v[36:37], v[38:39], 0, s[0:1]
	s_mov_b64 s[0:1], 0x3080
	s_waitcnt vmcnt(8)
	v_mov_b64_e32 v[28:29], v[136:137]
	v_mov_b64_e32 v[30:31], v[138:139]
	v_mov_b64_e32 v[32:33], v[140:141]
	v_mov_b64_e32 v[34:35], v[142:143]
	v_mov_b64_e32 v[64:65], v[144:145]
	v_mov_b64_e32 v[66:67], v[146:147]
	v_mov_b64_e32 v[68:69], v[148:149]
	v_mov_b64_e32 v[70:71], v[150:151]
	v_pk_add_f32 v[28:29], v[28:29], v[64:65]
	v_pk_add_f32 v[32:33], v[32:33], v[68:69]
	v_pk_add_f32 v[30:31], v[30:31], v[66:67]
	v_mov_b32_e32 v37, v32
	v_mov_b32_e32 v32, v29
	v_pk_add_f32 v[34:35], v[34:35], v[70:71]
	v_mov_b32_e32 v36, v28
	v_pk_mul_f32 v[28:29], v[32:33], v[62:63]
	v_mov_b32_e32 v32, v30
	v_pk_fma_f32 v[28:29], v[36:37], v[56:57], v[28:29]
	v_mov_b32_e32 v33, v34
	v_pk_fma_f32 v[28:29], v[32:33], v[58:59], v[28:29]
	v_mov_b32_e32 v34, v31
	v_pk_fma_f32 v[28:29], v[34:35], v[60:61], v[28:29]
	v_lshl_add_u64 v[32:33], v[38:39], 0, s[0:1]
	v_add_f32_e32 v28, v78, v28
	s_mov_b64 s[0:1], 0x3480
	v_add_f32_e32 v64, v28, v29
	s_nop 0
	v_lshl_add_u64 v[36:37], v[38:39], 0, s[0:1]
	s_mov_b64 s[0:1], 0x30c0
	s_waitcnt vmcnt(4)
	v_mov_b64_e32 v[28:29], v[152:153]
	v_mov_b64_e32 v[30:31], v[154:155]
	v_mov_b64_e32 v[32:33], v[156:157]
	v_mov_b64_e32 v[34:35], v[158:159]
	v_mov_b64_e32 v[56:57], v[160:161]
	v_mov_b64_e32 v[58:59], v[162:163]
	v_mov_b64_e32 v[60:61], v[164:165]
	v_mov_b64_e32 v[62:63], v[166:167]
	v_pk_add_f32 v[28:29], v[28:29], v[56:57]
	v_pk_add_f32 v[32:33], v[32:33], v[60:61]
	v_pk_add_f32 v[30:31], v[30:31], v[58:59]
	v_mov_b32_e32 v37, v32
	v_mov_b32_e32 v32, v29
	v_pk_add_f32 v[34:35], v[34:35], v[62:63]
	v_mov_b32_e32 v36, v28
	v_pk_mul_f32 v[28:29], v[32:33], v[54:55]
	v_mov_b32_e32 v32, v30
	v_pk_fma_f32 v[28:29], v[36:37], v[48:49], v[28:29]
	v_mov_b32_e32 v33, v34
	v_pk_fma_f32 v[28:29], v[32:33], v[50:51], v[28:29]
	v_mov_b32_e32 v34, v31
	v_pk_fma_f32 v[28:29], v[34:35], v[52:53], v[28:29]
	v_lshl_add_u64 v[32:33], v[38:39], 0, s[0:1]
	s_mov_b64 s[0:1], 0x34c0
	v_add_f32_e32 v28, v64, v28
	v_lshl_add_u64 v[48:49], v[38:39], 0, s[0:1]
	v_add_f32_e32 v52, v28, v29
	s_nop 0
	s_nop 0
	s_nop 0
	s_waitcnt vmcnt(0)
	v_mov_b64_e32 v[28:29], v[184:185]
	v_mov_b64_e32 v[30:31], v[186:187]
	v_mov_b64_e32 v[32:33], v[188:189]
	v_mov_b64_e32 v[34:35], v[190:191]
	v_mov_b64_e32 v[36:37], v[192:193]
	v_mov_b64_e32 v[38:39], v[194:195]
	v_mov_b64_e32 v[48:49], v[196:197]
	v_mov_b64_e32 v[50:51], v[198:199]
	v_pk_add_f32 v[28:29], v[28:29], v[36:37]
	v_pk_add_f32 v[32:33], v[32:33], v[48:49]
	v_pk_add_f32 v[22:23], v[30:31], v[38:39]
	v_pk_add_f32 v[30:31], v[34:35], v[50:51]
	v_mov_b32_e32 v35, v32
	v_mov_b32_e32 v32, v29
	v_mov_b32_e32 v34, v28
	v_pk_mul_f32 v[28:29], v[32:33], v[46:47]
	v_mov_b32_e32 v32, v22
	v_pk_fma_f32 v[28:29], v[34:35], v[44:45], v[28:29]
	v_mov_b32_e32 v33, v30
	v_pk_fma_f32 v[28:29], v[32:33], v[42:43], v[28:29]
	v_mov_b32_e32 v30, v23
	v_pk_fma_f32 v[22:23], v[30:31], v[40:41], v[28:29]
	s_nop 0
	v_add_f32_e32 v22, v52, v22
	v_add_f32_e32 v22, v22, v23
	ds_bpermute_b32 v15, v15, v22
	s_waitcnt lgkmcnt(0)
	v_add_f32_e32 v22, v22, v15

.LBB0_847:
	s_mov_b64 s[0:1], 0x2800
	v_add_co_u32_e32 v22, vcc, 0x2000, v38
	v_lshl_add_u64 v[32:33], v[38:39], 0, s[0:1]
	s_mov_b64 s[0:1], 0x2c00
	v_addc_co_u32_e32 v23, vcc, 0, v39, vcc
	v_lshl_add_u64 v[36:37], v[38:39], 0, s[0:1]
	s_nop 0
	s_nop 0
	s_mov_b64 s[0:1], 0x2840
	s_waitcnt vmcnt(16)
	v_mov_b64_e32 v[28:29], v[136:137]
	v_mov_b64_e32 v[30:31], v[138:139]
	v_mov_b64_e32 v[32:33], v[140:141]
	v_mov_b64_e32 v[34:35], v[142:143]
	v_mov_b64_e32 v[78:79], v[144:145]
	v_mov_b64_e32 v[80:81], v[146:147]
	v_mov_b64_e32 v[82:83], v[148:149]
	v_mov_b64_e32 v[84:85], v[150:151]
	global_load_dwordx4 v[136:139], v[232:233], off offset:64
	global_load_dwordx4 v[140:143], v[232:233], off offset:80
	global_load_dwordx4 v[144:147], v[232:233], off offset:1088
	global_load_dwordx4 v[148:151], v[232:233], off offset:1104
	v_pk_add_f32 v[28:29], v[28:29], v[78:79]
	v_pk_add_f32 v[32:33], v[32:33], v[82:83]
	v_pk_add_f32 v[30:31], v[30:31], v[80:81]
	v_mov_b32_e32 v37, v32
	v_mov_b32_e32 v32, v29
	v_pk_add_f32 v[34:35], v[34:35], v[84:85]
	v_mov_b32_e32 v36, v28
	v_pk_mul_f32 v[28:29], v[32:33], v[70:71]
	v_mov_b32_e32 v32, v30
	v_pk_fma_f32 v[28:29], v[36:37], v[64:65], v[28:29]
	v_mov_b32_e32 v33, v34
	v_pk_fma_f32 v[28:29], v[32:33], v[66:67], v[28:29]
	v_mov_b32_e32 v34, v31
	v_pk_fma_f32 v[28:29], v[34:35], v[68:69], v[28:29]
	v_lshl_add_u64 v[32:33], v[38:39], 0, s[0:1]
	v_add_f32_e32 v27, 0, v28
	s_mov_b64 s[0:1], 0x2c40
	v_add_f32_e32 v27, v27, v29
	s_nop 0
	v_lshl_add_u64 v[36:37], v[38:39], 0, s[0:1]
	s_mov_b64 s[0:1], 0x2880
	s_waitcnt vmcnt(16)
	v_mov_b64_e32 v[28:29], v[152:153]
	v_mov_b64_e32 v[30:31], v[154:155]
	v_mov_b64_e32 v[32:33], v[156:157]
	v_mov_b64_e32 v[34:35], v[158:159]
	v_mov_b64_e32 v[78:79], v[160:161]
	v_mov_b64_e32 v[80:81], v[162:163]
	v_mov_b64_e32 v[82:83], v[164:165]
	v_mov_b64_e32 v[84:85], v[166:167]
	global_load_dwordx4 v[152:155], v[232:233], off offset:128
	global_load_dwordx4 v[156:159], v[232:233], off offset:144
	global_load_dwordx4 v[160:163], v[232:233], off offset:1152
	global_load_dwordx4 v[164:167], v[232:233], off offset:1168
	v_pk_add_f32 v[28:29], v[28:29], v[78:79]
	v_pk_add_f32 v[32:33], v[32:33], v[82:83]
	v_pk_add_f32 v[30:31], v[30:31], v[80:81]
	v_mov_b32_e32 v37, v32
	v_mov_b32_e32 v32, v29
	v_pk_add_f32 v[34:35], v[34:35], v[84:85]
	v_mov_b32_e32 v36, v28
	v_pk_mul_f32 v[28:29], v[32:33], v[62:63]
	v_mov_b32_e32 v32, v30
	v_pk_fma_f32 v[28:29], v[36:37], v[56:57], v[28:29]
	v_mov_b32_e32 v33, v34
	v_pk_fma_f32 v[28:29], v[32:33], v[58:59], v[28:29]
	v_mov_b32_e32 v34, v31
	v_pk_fma_f32 v[28:29], v[34:35], v[60:61], v[28:29]
	v_lshl_add_u64 v[32:33], v[38:39], 0, s[0:1]
	v_add_f32_e32 v27, v27, v28
	s_mov_b64 s[0:1], 0x2c80
	v_add_f32_e32 v27, v27, v29
	s_nop 0
	v_lshl_add_u64 v[36:37], v[38:39], 0, s[0:1]
	s_mov_b64 s[0:1], 0x28c0
	s_waitcnt vmcnt(16)
	v_mov_b64_e32 v[28:29], v[184:185]
	v_mov_b64_e32 v[30:31], v[186:187]
	v_mov_b64_e32 v[32:33], v[188:189]
	v_mov_b64_e32 v[34:35], v[190:191]
	v_mov_b64_e32 v[78:79], v[192:193]
	v_mov_b64_e32 v[80:81], v[194:195]
	v_mov_b64_e32 v[82:83], v[196:197]
	v_mov_b64_e32 v[84:85], v[198:199]
	global_load_dwordx4 v[184:187], v[232:233], off offset:192
	global_load_dwordx4 v[188:191], v[232:233], off offset:208
	global_load_dwordx4 v[192:195], v[232:233], off offset:1216
	global_load_dwordx4 v[196:199], v[232:233], off offset:1232
	v_pk_add_f32 v[28:29], v[28:29], v[78:79]
	v_pk_add_f32 v[32:33], v[32:33], v[82:83]
	v_pk_add_f32 v[30:31], v[30:31], v[80:81]
	v_mov_b32_e32 v37, v32
	v_mov_b32_e32 v32, v29
	v_pk_add_f32 v[34:35], v[34:35], v[84:85]
	v_mov_b32_e32 v36, v28
	v_pk_mul_f32 v[28:29], v[32:33], v[54:55]
	v_mov_b32_e32 v32, v30
	v_pk_fma_f32 v[28:29], v[36:37], v[48:49], v[28:29]
	v_mov_b32_e32 v33, v34
	v_pk_fma_f32 v[28:29], v[32:33], v[50:51], v[28:29]
	v_mov_b32_e32 v34, v31
	v_pk_fma_f32 v[28:29], v[34:35], v[52:53], v[28:29]
	v_lshl_add_u64 v[32:33], v[38:39], 0, s[0:1]
	v_add_f32_e32 v27, v27, v28
	s_mov_b64 s[0:1], 0x2cc0
	v_add_f32_e32 v27, v27, v29
	s_nop 0
	v_lshl_add_u64 v[36:37], v[38:39], 0, s[0:1]
	s_waitcnt vmcnt(16)
	v_mov_b64_e32 v[28:29], v[200:201]
	v_mov_b64_e32 v[30:31], v[202:203]
	v_mov_b64_e32 v[32:33], v[204:205]
	v_mov_b64_e32 v[34:35], v[206:207]
	v_mov_b64_e32 v[78:79], v[208:209]
	v_mov_b64_e32 v[80:81], v[210:211]
	v_mov_b64_e32 v[82:83], v[212:213]
	v_mov_b64_e32 v[84:85], v[214:215]
	v_pk_add_f32 v[28:29], v[28:29], v[78:79]
	v_pk_add_f32 v[32:33], v[32:33], v[82:83]
	v_pk_add_f32 v[22:23], v[30:31], v[80:81]
	v_pk_add_f32 v[30:31], v[34:35], v[84:85]
	v_mov_b32_e32 v35, v32
	v_mov_b32_e32 v32, v29
	v_mov_b32_e32 v34, v28
	v_pk_mul_f32 v[28:29], v[32:33], v[46:47]
	v_mov_b32_e32 v32, v22
	v_pk_fma_f32 v[28:29], v[34:35], v[44:45], v[28:29]
	v_mov_b32_e32 v33, v30
	v_pk_fma_f32 v[28:29], v[32:33], v[42:43], v[28:29]
	v_mov_b32_e32 v30, v23
	v_pk_fma_f32 v[22:23], v[30:31], v[40:41], v[28:29]
	s_nop 0
	v_add_f32_e32 v22, v27, v22
	v_add_f32_e32 v22, v22, v23
	ds_bpermute_b32 v23, v15, v22
	s_waitcnt lgkmcnt(0)
	v_add_f32_e32 v27, v22, v23
	s_cmp_lg_u32 s46, 7
	v_mov_b32_e32 v22, 0xff800000
	s_cbranch_scc0 .LBB0_793
	s_branch .LBB0_794
